# workgroups that finished one of the 8 longest attention units skip the end-of-queue steal attempts
# baseline (speedup 1.0000x reference)
; __global__ void __launch_bounds__(512) fwd_megakernel(Args a) {
;     ...
;                     if (idx < len) { slot = (myq << 16) | idx; break; } myq = (myq + 1) & 7; ++tries; }
;                 qslot[0] = slot; }
;             __syncthreads();
;             const int slot = qslot[0];
;             if (slot < 0) break;
;             const int q = slot >> 16, idx = slot & 0xffff;
;             int ub, uh, uq; bool isdf = true;
;             if (q < 4) { ub = q >> 1; uh = 3 - (q & 1); uq = 63 - idx; }
;             else { const int y = q - 4;
;                 if (idx < 64) { ub = y >> 1; uh = 1 - (y & 1); uq = 63 - idx; }
;                 else { const int v = idx - 64; const int bh = 4 * y + (v & 3); ub = bh >> 3; uh = bh & 7; uq = 31 - (v >> 2); isdf = false; } }
.LBB0_367:
	s_and_b64 vcc, exec, s[6:7]
	s_cbranch_vccz .LBB0_363
	s_cmp_lt_u32 s5, 8
	s_cbranch_scc0 .Lhv_more
	v_mov_b32_e32 v239, 8
.Lhv_more:
	s_bfe_u32 s0, s4, 0x10010
	s_lshr_b32 s14, s4, 17
	s_xor_b32 s16, s0, 3
	s_cmp_lt_u32 s5, 32
	s_cbranch_scc1 .Lhv_ok
	s_add_i32 s5, s5, 14
